# conversion pipeline shift: W2(l) converted in layer l's own gemm3 idle half-round (last layer's slot was empty), prologue 28544 -> 20352 items
# speedup vs baseline: 1.0106x; 1.0001x over previous
; #define LAS __attribute__((address_space(3)))
; #define CV_MAP(g_, l_, it_) do { (l_) = lfix; \
;         if (MODE == 2) (it_) = CV_S0 + base + (g_); \
;         else if (MODE == 1) (it_) = cv_ritem(g_); \
;         else if ((g_) < CV_NR) (it_) = cv_ritem(g_); \
;         else { const int q_ = ((g_) - CV_NR) / CV_RPRO; (l_) = 1 + q_; (it_) = cv_ritem(CV_DEFER + ((g_) - CV_NR) - q_ * CV_RPRO); } } while (0)
; template <int MODE>
; __device__ __forceinline__ void cv_jobs(const Frame& F, const Args& a, int lfix, int base, int njobs, int w, int nw) {
;     LAS float* scr = (LAS float*)(F.lds + RING_OFF + F.wave * 16384);
;     f32x4 sa[8], sb[8];
;     ...
;     for (int g = w; g < njobs; g += 2 * nw) {
;         const int g1 = g + nw; int l, it, l1, it1; CV_MAP(g, l, it); CV_MAP(g1, l1, it1);
;         cv_load(a, l, it, F.lane, sa);
;         if (g1 < njobs) cv_load(a, l1, it1, F.lane, sb);
;         cv_store(a, sa, scr, l, it, F.lane);
;         if (g1 < njobs) cv_store(a, sb, scr, l1, it1, F.lane);
;     }
; __device__ __forceinline__ void p0_prologue(const Frame& F0, const Args& a0) {
;     ...
;     for (int rep = 0; rep < REP_PT; ++rep) cv_jobs<0>(F, a, 0, 0, CV_NR + (DEPTH - 1) * CV_RPRO, F.vcu * NWAVES + F.wave, F.G * NWAVES);
.LBB0_7:
	s_or_b64 exec, exec, s[0:1]
	v_writelane_b32 v221, s40, 34
	s_lshr_b32 s95, s4, 6
	s_mov_b64 s[4:5], s[64:65]
	v_writelane_b32 v221, s41, 35
	v_writelane_b32 v221, s42, 36
	v_writelane_b32 v221, s43, 37
	v_writelane_b32 v221, s44, 38
	v_writelane_b32 v221, s45, 39
	v_writelane_b32 v221, s46, 40
	v_writelane_b32 v221, s47, 41
	s_cmp_lt_i32 s64, 1
	v_writelane_b32 v221, s4, 42
	s_cselect_b64 s[0:1], -1, 0
	s_cmp_gt_i32 s65, 0
	v_writelane_b32 v221, s5, 43
	s_cselect_b64 s[2:3], -1, 0
	v_writelane_b32 v221, s6, 44
	s_and_b64 s[0:1], s[0:1], s[2:3]
	v_writelane_b32 v221, s7, 45
	s_andn2_b64 vcc, exec, s[0:1]
	v_writelane_b32 v221, s38, 46
	s_nop 1
	v_writelane_b32 v221, s39, 47
	s_cbranch_vccnz .LBB0_110
	s_mov_b32 s2, s94
	s_mov_b32 s21, s95
	s_mov_b32 s10, s92
	s_mov_b32 s14, s93
	v_readlane_b32 s48, v221, 0
	v_mbcnt_lo_u32_b32 v67, -1, 0
	v_mbcnt_hi_u32_b32 v67, -1, v67
	v_readlane_b32 s49, v221, 1
	s_mov_b64 s[2:3], s[48:49]
	v_readlane_b32 s50, v221, 2
	v_readlane_b32 s51, v221, 3
	v_readlane_b32 s52, v221, 4
	v_readlane_b32 s53, v221, 5
	s_mov_b64 s[30:31], s[50:51]
	s_mov_b64 s[2:3], s[52:53]
	v_readlane_b32 s54, v221, 6
	v_readlane_b32 s55, v221, 7
	v_readlane_b32 s56, v221, 8
	v_readlane_b32 s57, v221, 9
	v_readlane_b32 s58, v221, 10
	v_readlane_b32 s59, v221, 11
	v_readlane_b32 s60, v221, 12
	v_readlane_b32 s61, v221, 13
	s_mov_b64 s[34:35], s[54:55]
	s_mov_b64 s[18:19], s[56:57]
	s_mov_b64 s[16:17], s[58:59]
	s_mov_b64 s[2:3], s[60:61]
	v_readlane_b32 s64, v221, 16
	v_readlane_b32 s62, v221, 14
	v_readlane_b32 s63, v221, 15
	v_readlane_b32 s65, v221, 17
	s_mov_b64 s[2:3], s[62:63]
	s_mov_b64 s[4:5], s[64:65]
	v_readlane_b32 s66, v221, 18
	v_readlane_b32 s67, v221, 19
	s_mov_b64 s[4:5], s[66:67]
	v_readlane_b32 s68, v221, 20
	v_readlane_b32 s69, v221, 21
	s_mov_b64 s[4:5], s[68:69]
	v_readlane_b32 s70, v221, 22
	v_readlane_b32 s71, v221, 23
	s_mov_b64 s[4:5], s[70:71]
	v_readlane_b32 s72, v221, 24
	v_readlane_b32 s73, v221, 25
	s_mov_b64 s[4:5], s[72:73]
	v_readlane_b32 s74, v221, 26
	v_readlane_b32 s75, v221, 27
	v_readlane_b32 s76, v221, 28
	v_readlane_b32 s77, v221, 29
	s_mov_b64 s[4:5], s[74:75]
	s_mov_b64 s[6:7], s[76:77]
	v_readlane_b32 s78, v221, 30
	v_readlane_b32 s79, v221, 31
	s_mov_b64 s[6:7], s[78:79]
	s_mov_b64 s[8:9], s[40:41]
	s_mov_b64 s[12:13], s[42:43]
	s_lshl_b32 s11, s14, 3
	s_add_i32 s11, s11, s21
	s_mov_b64 s[12:13], s[44:45]
	s_mov_b64 s[68:69], s[46:47]
	s_cmpk_gt_i32 s11, 0x4f7f
	v_lshlrev_b32_e32 v68, 2, v67
	s_cbranch_scc1 .LBB0_70
	s_lshl_b32 s12, s21, 14
	s_lshl_b32 s15, s10, 3
	s_add_i32 s12, s12, 0
	s_lshl_b32 s22, s10, 4
	s_add_u32 s23, s68, 0x10000000
	s_addc_u32 s24, s69, 0
	v_lshlrev_b32_e32 v1, 3, v67
	v_ashrrev_i32_e32 v69, 3, v67
	v_and_b32_e32 v66, 56, v1
	s_add_u32 s25, s68, 0x8000000
	v_mul_u32_u24_e32 v1, 0x84, v66
	v_lshlrev_b32_e32 v2, 2, v69
	s_addc_u32 s26, s69, 0
	v_add_u32_e32 v72, 8, v69
	v_add3_u32 v75, s12, v1, v2
	v_lshlrev_b32_e32 v1, 1, v69
	s_add_u32 s27, s68, 0x6000000
	v_add_u32_e32 v73, 16, v69
	v_and_b32_e32 v76, 62, v1
	v_lshlrev_b32_e32 v1, 1, v72
	s_addc_u32 s28, s69, 0
	v_and_b32_e32 v0, 28, v68
	v_add_u32_e32 v74, 24, v69
	v_and_b32_e32 v77, 62, v1
	v_lshlrev_b32_e32 v1, 1, v73
	s_add_u32 s29, s68, 0x400000
	v_lshl_add_u32 v70, v0, 2, s12
	s_movk_i32 s13, 0x84
	v_and_b32_e32 v78, 62, v1
	v_lshlrev_b32_e32 v1, 1, v74
	s_addc_u32 s33, s69, 0
	s_add_i32 s12, s11, s15
	s_mov_b32 s71, 0
	v_mov_b32_e32 v65, 0
	v_mul_lo_u32 v71, v69, s13
	v_and_b32_e32 v79, 62, v1
	s_add_i32 s36, s11, 0xc020
	s_add_i32 s37, s15, 0xfffff020
	s_add_i32 s38, s12, 0xffffc020
	s_add_i32 s39, s15, 0xe60
	s_mov_b32 s40, 0x10000
	s_mov_b32 s41, 0x20000
	s_mov_b32 s42, 0x30000
	s_mov_b32 s43, 0x40000
	s_mov_b32 s44, 0x50000
	s_mov_b32 s45, 0x60000
	s_mov_b64 s[72:73], 0x70000
	s_mov_b64 s[74:75], 0x1c0000
	s_movk_i32 s46, 0x5880
	s_mov_b64 s[76:77], 0x40000
	s_movk_i32 s47, 0x500
	v_lshlrev_b32_e32 v64, 2, v0
	s_branch .LBB0_11
.LBB0_10:
	s_add_i32 s11, s11, s22
	s_add_i32 s36, s36, s22
	s_add_i32 s38, s38, s22
	s_cmpk_lt_i32 s11, 0x4f80
	s_cbranch_scc0 .LBB0_70
.LBB0_11:
	s_cmpk_gt_i32 s11, 0x1fdf
	s_mov_b64 s[12:13], -1
	s_cbranch_scc0 .LBB0_13
	s_add_i32 s12, s11, 0xffffe020
	s_mov_b32 s70, 1
	s_cmpk_lt_i32 s12, 0xfe0
	s_cbranch_scc1 .Lmy_cvqa
	s_addk_i32 s12, 0xf020
	s_mov_b32 s70, 2
	s_cmpk_lt_i32 s12, 0xfe0
	s_cbranch_scc1 .Lmy_cvqa
	s_addk_i32 s12, 0xf020
	s_mov_b32 s70, 3
.Lmy_cvqa:
	s_add_i32 s49, s12, 0x1000
	s_mov_b64 s[80:81], s[70:71]
	s_cbranch_execnz .LBB0_15
	s_branch .LBB0_14

; #define CV_MAP(g_, l_, it_) do { (l_) = lfix; \
;         if (MODE == 2) (it_) = CV_S0 + base + (g_); \
;         else if (MODE == 1) (it_) = cv_ritem(g_); \
;         else if ((g_) < CV_NR) (it_) = cv_ritem(g_); \
;         else { const int q_ = ((g_) - CV_NR) / CV_RPRO; (l_) = 1 + q_; (it_) = cv_ritem(CV_DEFER + ((g_) - CV_NR) - q_ * CV_RPRO); } } while (0)
; template <int MODE>
; __device__ __forceinline__ void cv_jobs(const Frame& F, const Args& a, int lfix, int base, int njobs, int w, int nw) {
;     ...
;         const int g1 = g + nw; int l, it, l1, it1; CV_MAP(g, l, it); CV_MAP(g1, l1, it1);
.LBB0_15:
	s_add_i32 s51, s15, s11
	s_cmpk_gt_i32 s51, 0x1fdf
	s_mov_b64 s[12:13], -1
	s_cbranch_scc0 .LBB0_17
	s_add_i32 s12, s51, 0xffffe020
	s_mov_b32 s70, 1
	s_cmpk_lt_i32 s12, 0xfe0
	s_cbranch_scc1 .Lmy_cvqb
	s_addk_i32 s12, 0xf020
	s_mov_b32 s70, 2
	s_cmpk_lt_i32 s12, 0xfe0
	s_cbranch_scc1 .Lmy_cvqb
	s_addk_i32 s12, 0xf020
	s_mov_b32 s70, 3
.Lmy_cvqb:
	s_add_i32 s48, s12, 0x1000
	s_mov_b64 s[78:79], s[70:71]
	s_cbranch_execz .LBB0_18
	s_branch .LBB0_19

; __device__ __forceinline__ void cv_load(const Args& a, int l, int it, int lane, f32x4 (&wv)[8]) {
;     ...
;     else if (it < CV_B) p0_item_load(a.in[I_WOUT] + (size_t)l * DM * DM, DM, it - CV_A, lane, wv);
;     else if (it < CV_C) p0_item_load(a.in[I_W1] + (size_t)l * DM * DFF, DFF, it - CV_B, lane, wv);
;     else p0_item_load(a.in[I_W2] + (size_t)l * DFF * DM, DM, it - CV_C, lane, wv);
; template <int MODE>
; __device__ __forceinline__ void cv_jobs(const Frame& F, const Args& a, int lfix, int base, int njobs, int w, int nw) {
;     ...
;         if (g1 < njobs) cv_load(a, l1, it1, F.lane, sb);
;         cv_store(a, sa, scr, l, it, F.lane);
;         if (g1 < njobs) cv_store(a, sb, scr, l1, it1, F.lane);
.LBB0_31:
	s_waitcnt vmcnt(0)
	global_load_dwordx4 v[60:63], v[60:61], off nt
	s_cmpk_lt_i32 s51, 0x4f80
	s_cselect_b64 s[82:83], -1, 0
	s_cmpk_gt_i32 s51, 0x4f7f
	s_cbranch_scc1 .LBB0_47
	s_cmpk_gt_i32 s48, 0x161f
	s_mov_b64 s[84:85], -1
	s_cbranch_scc0 .LBB0_42
	s_cmpk_gt_u32 s48, 0x1e1f
	s_cbranch_scc0 .LBB0_39
	s_lshl_b64 s[84:85], s[78:79], 26
	s_cmpk_gt_u32 s48, 0x3e1f
	s_mov_b64 s[86:87], -1
	s_cbranch_scc0 .LBB0_36
	s_add_u32 s51, s8, s84
	s_addc_u32 s53, s9, s85
	s_add_i32 s52, s48, 0xffffc1e0
	s_and_b32 s54, s52, 0xffffffc0
	s_lshl_b32 s52, s52, 7
	v_add_u32_e32 v2, s54, v69
	s_and_b32 s52, s52, 0x1f80
	s_add_u32 s52, s51, s52
	v_add_u32_e32 v10, 24, v2
	s_addc_u32 s53, s53, 0
	v_ashrrev_i32_e32 v11, 31, v10
	v_lshl_add_u64 v[6:7], s[52:53], 0, v[64:65]
	v_lshlrev_b64 v[10:11], 13, v[10:11]
	v_lshl_add_u64 v[12:13], v[6:7], 0, v[10:11]
	v_add_u32_e32 v10, 32, v2
	v_ashrrev_i32_e32 v11, 31, v10
	v_lshlrev_b64 v[10:11], 13, v[10:11]
	v_lshl_add_u64 v[16:17], v[6:7], 0, v[10:11]
	v_add_u32_e32 v10, 40, v2
	v_ashrrev_i32_e32 v11, 31, v10
	v_ashrrev_i32_e32 v3, 31, v2
	v_lshlrev_b64 v[10:11], 13, v[10:11]
	v_lshlrev_b64 v[0:1], 13, v[2:3]
	v_add_u32_e32 v4, 8, v2
	v_add_u32_e32 v8, 16, v2
	v_lshl_add_u64 v[20:21], v[6:7], 0, v[10:11]
	v_add_u32_e32 v10, 48, v2
	v_add_u32_e32 v2, 56, v2
	v_ashrrev_i32_e32 v5, 31, v4
	v_ashrrev_i32_e32 v9, 31, v8
	v_ashrrev_i32_e32 v11, 31, v10
	v_ashrrev_i32_e32 v3, 31, v2
	v_lshlrev_b64 v[4:5], 13, v[4:5]
	v_lshlrev_b64 v[8:9], 13, v[8:9]
	v_lshlrev_b64 v[10:11], 13, v[10:11]
	v_lshlrev_b64 v[2:3], 13, v[2:3]
	v_lshl_add_u64 v[0:1], v[6:7], 0, v[0:1]
	v_lshl_add_u64 v[4:5], v[6:7], 0, v[4:5]
	v_lshl_add_u64 v[8:9], v[6:7], 0, v[8:9]
	v_lshl_add_u64 v[24:25], v[6:7], 0, v[10:11]
	v_lshl_add_u64 v[28:29], v[6:7], 0, v[2:3]
	s_mov_b64 s[86:87], 0

; #define LAS __attribute__((address_space(3)))
; #define CV_MAP(g_, l_, it_) do { (l_) = lfix; \
;         if (MODE == 2) (it_) = CV_S0 + base + (g_); \
;         else if (MODE == 1) (it_) = cv_ritem(g_); \
;         else if ((g_) < CV_NR) (it_) = cv_ritem(g_); \
;         else { const int q_ = ((g_) - CV_NR) / CV_RPRO; (l_) = 1 + q_; (it_) = cv_ritem(CV_DEFER + ((g_) - CV_NR) - q_ * CV_RPRO); } } while (0)
; template <int MODE>
; __device__ __forceinline__ void cv_jobs(const Frame& F, const Args& a, int lfix, int base, int njobs, int w, int nw) {
;     LAS float* scr = (LAS float*)(F.lds + RING_OFF + F.wave * 16384);
;     f32x4 sa[8], sb[8];
;     ...
;     for (int g = w; g < njobs; g += 2 * nw) {
;         const int g1 = g + nw; int l, it, l1, it1; CV_MAP(g, l, it); CV_MAP(g1, l1, it1);
;         cv_load(a, l, it, F.lane, sa);
;         if (g1 < njobs) cv_load(a, l1, it1, F.lane, sb);
;         cv_store(a, sa, scr, l, it, F.lane);
;         if (g1 < njobs) cv_store(a, sb, scr, l1, it1, F.lane);
;     }
; template <int MODE>
; __device__ __forceinline__ void cv_deferred(const Frame& F0, const Args& a0, int lfix, int base, int njobs, int w, int nw) {
;     const Frame F = relaunder(F0); const Args a = relaunder_args(a0);
;     cv_jobs<MODE>(F, a, lfix, base, njobs, w, nw);
; __global__ void __launch_bounds__(NTHREADS, 2) fwd(Args args) {
;     ...
;             if (!last && rep == 0 && CV_DEFER > 0 && F.bx >= 128) { __syncthreads(); cv_deferred<1>(F, args, l + 1, 0, CV_DEFER, (F.bx - 128) * NWAVES + F.wave, 128 * NWAVES); }
.LBB0_981:
	v_readlane_b32 s2, v220, 0
	v_readlane_b32 s3, v220, 1
	s_and_b64 vcc, exec, s[2:3]
	s_cbranch_vccnz .LBB0_1037
	s_mov_b32 s2, s92
	s_mov_b32 s3, s93
	s_mov_b32 s4, s94
	s_mov_b32 s12, s95
	v_readlane_b32 s48, v221, 0
	s_waitcnt vmcnt(0)
	s_barrier
	v_mbcnt_lo_u32_b32 v0, -1, 0
	v_mbcnt_hi_u32_b32 v0, -1, v0
	v_readlane_b32 s49, v221, 1
	s_mov_b64 s[2:3], s[48:49]
	v_readlane_b32 s50, v221, 2
	v_readlane_b32 s51, v221, 3
	s_mov_b64 s[2:3], s[50:51]
	v_readlane_b32 s52, v221, 4
	v_readlane_b32 s53, v221, 5
	s_mov_b64 s[2:3], s[52:53]
	v_readlane_b32 s54, v221, 6
	v_readlane_b32 s55, v221, 7
	s_mov_b64 s[2:3], s[54:55]
	v_readlane_b32 s56, v221, 8
	v_readlane_b32 s57, v221, 9
	s_mov_b64 s[2:3], s[56:57]
	v_readlane_b32 s58, v221, 10
	v_readlane_b32 s59, v221, 11
	s_mov_b64 s[2:3], s[58:59]
	v_readlane_b32 s60, v221, 12
	v_readlane_b32 s61, v221, 13
	v_readlane_b32 s62, v221, 14
	v_readlane_b32 s63, v221, 15
	s_mov_b64 s[2:3], s[60:61]
	s_mov_b64 s[4:5], s[62:63]
	v_readlane_b32 s48, v221, 16
	v_readlane_b32 s49, v221, 17
	s_mov_b64 s[2:3], s[48:49]
	v_readlane_b32 s50, v221, 18
	v_readlane_b32 s51, v221, 19
	s_mov_b64 s[2:3], s[50:51]
	v_readlane_b32 s52, v221, 20
	v_readlane_b32 s53, v221, 21
	s_mov_b64 s[2:3], s[52:53]
	v_readlane_b32 s54, v221, 22
	v_readlane_b32 s55, v221, 23
	s_mov_b64 s[2:3], s[54:55]
	v_readlane_b32 s56, v221, 24
	v_readlane_b32 s57, v221, 25
	s_mov_b64 s[2:3], s[56:57]
	v_readlane_b32 s58, v221, 26
	v_readlane_b32 s59, v221, 27
	v_readlane_b32 s60, v221, 28
	v_readlane_b32 s61, v221, 29
	s_mov_b64 s[6:7], s[58:59]
	s_mov_b64 s[2:3], s[60:61]
	v_readlane_b32 s62, v221, 30
	v_readlane_b32 s63, v221, 31
	s_mov_b64 s[8:9], s[62:63]
	s_mov_b64 s[10:11], s[40:41]
	s_mov_b64 s[2:3], s[42:43]
	s_mov_b64 s[2:3], s[44:45]
	v_readlane_b32 s14, v220, 2
	v_readlane_b32 s15, v220, 3
	s_mov_b64 s[2:3], s[46:47]
	s_andn2_b64 vcc, exec, s[14:15]
	s_cbranch_vccnz .LBB0_1037
	s_add_i32 s84, s24, 1
	s_lshl_b32 s12, s12, 14
	s_lshl_b64 s[14:15], s[84:85], 26
	s_lshl_b64 s[16:17], s[84:85], 24
	s_lshl_b64 s[18:19], s[84:85], 25
	s_lshl_b64 s[22:23], s[84:85], 23
	s_add_i32 s12, s12, 0
	s_add_u32 s10, s10, s14
	s_addc_u32 s11, s11, s15
	s_sub_u32 s10, s10, 0x4000000
	s_subb_u32 s11, s11, 0
	s_add_u32 s8, s8, s14
	s_addc_u32 s9, s9, s15
	s_add_u32 s6, s6, s16
	s_mul_i32 s24, s84, 0x2c40000
	s_addc_u32 s7, s7, s17
	s_mul_hi_u32 s13, s84, 0x2c40000
	v_lshlrev_b32_e32 v1, 4, v0
	s_add_u32 s4, s4, s24
	v_and_b32_e32 v160, 0x70, v1
	s_addc_u32 s5, s5, s13
	v_ashrrev_i32_e32 v80, 3, v0
	v_lshl_add_u64 v[70:71], s[4:5], 0, v[160:161]
	s_movk_i32 s4, 0x84
	v_lshlrev_b32_e32 v0, 3, v0
	v_mul_lo_u32 v82, v80, s4
	v_and_b32_e32 v0, 56, v0
	s_add_u32 s4, s2, s18
	v_lshl_add_u64 v[64:65], s[10:11], 0, v[160:161]
	v_lshl_add_u64 v[66:67], s[8:9], 0, v[160:161]
	v_lshl_add_u64 v[68:69], s[6:7], 0, v[160:161]
	v_add_u32_e32 v81, s12, v160
	v_lshlrev_b32_e32 v160, 1, v0
	s_addc_u32 s5, s3, s19
	v_mul_u32_u24_e32 v2, 0x84, v0
	v_lshl_add_u64 v[0:1], s[4:5], 0, v[160:161]
	s_mov_b64 s[4:5], 0xe000000
	v_lshl_add_u64 v[72:73], v[0:1], 0, s[4:5]
	s_mov_b64 s[4:5], 0x8000000
	v_lshlrev_b32_e32 v3, 2, v80
	v_lshl_add_u64 v[74:75], v[0:1], 0, s[4:5]
	s_add_u32 s4, s2, s22
	s_mul_i32 s26, s84, 0x1700000
	v_add_u32_e32 v83, 8, v80
	v_add3_u32 v86, s12, v2, v3
	v_lshlrev_b32_e32 v2, 1, v80
	s_addc_u32 s5, s3, s23
	s_mul_hi_u32 s25, s84, 0x1700000
	v_add_u32_e32 v84, 16, v80
	v_and_b32_e32 v87, 62, v2
	v_lshlrev_b32_e32 v2, 1, v83
	s_add_u32 s2, s2, s26
	v_add_u32_e32 v85, 24, v80
	v_and_b32_e32 v88, 62, v2
	v_lshlrev_b32_e32 v2, 1, v84
	v_lshl_add_u64 v[0:1], s[4:5], 0, v[160:161]
	s_mov_b64 s[4:5], 0x6000000
	s_addc_u32 s3, s3, s25
	v_and_b32_e32 v89, 62, v2
	v_lshlrev_b32_e32 v2, 1, v85
	v_lshl_add_u64 v[76:77], v[0:1], 0, s[4:5]
	v_lshl_add_u64 v[0:1], s[2:3], 0, v[160:161]
	s_mov_b64 s[2:3], 0x400000
	v_and_b32_e32 v90, 62, v2
	v_lshl_add_u64 v[78:79], v[0:1], 0, s[2:3]
	v_readlane_b32 s8, v220, 8
	s_movk_i32 s14, 0x5880
	s_movk_i32 s15, 0x500
	s_mov_b64 s[16:17], 0x1c0000
	s_mov_b64 s[18:19], 0x70000
	s_cmp_lg_u64 s[76:77], 0
	s_cselect_b32 s4, 0x1000, 0
	s_add_i32 s8, s8, s4
	s_branch .LBB0_985

; __device__ __forceinline__ void p0_item_load(const float* W, int N, int item, int lane, f32x4 (&wv)[8]) {
;     const int nblk = N / 32, kb = item / nblk, nb = item % nblk, k0 = 64 * kb, n0 = 32 * nb;
; #pragma unroll
;     for (int i = 0; i < 8; ++i) wv[i] = *(const f32x4*)(W + (size_t)(k0 + 8 * i + (lane >> 3)) * N + n0 + 4 * (lane & 7));
; __device__ __forceinline__ void cv_load(const Args& a, int l, int it, int lane, f32x4 (&wv)[8]) {
;     ...
;     else if (it < CV_B) p0_item_load(a.in[I_WOUT] + (size_t)l * DM * DM, DM, it - CV_A, lane, wv);
;     else if (it < CV_C) p0_item_load(a.in[I_W1] + (size_t)l * DM * DFF, DFF, it - CV_B, lane, wv);
;     else p0_item_load(a.in[I_W2] + (size_t)l * DFF * DM, DM, it - CV_C, lane, wv);
.LBB0_985:
	s_add_i32 s9, s8, 0x3e20
	s_add_i32 s2, s8, 0x6c40
	s_cmpk_lt_i32 s9, 0x1000
	s_cselect_b32 s10, s9, s2
	s_cmpk_gt_i32 s10, 0x161f
	s_cselect_b64 s[2:3], -1, 0
	s_mov_b64 s[4:5], -1
	s_and_b64 vcc, exec, s[2:3]
	s_cbranch_vccz .LBB0_995
	s_cmpk_gt_u32 s10, 0x1e1f
	s_cbranch_scc0 .LBB0_992
	s_cmpk_gt_u32 s10, 0x3e1f
	s_cbranch_scc0 .LBB0_989
	s_add_i32 s4, s10, 0xffffc1e0
	s_and_b32 s5, s4, 0xffffffc0
	s_waitcnt vmcnt(6)
	v_add_u32_e32 v32, s5, v80
	s_lshl_b32 s4, s4, 7
	s_and_b32 s84, s4, 0x1f80
	v_ashrrev_i32_e32 v33, 31, v32
	v_lshl_add_u64 v[34:35], v[64:65], 0, s[84:85]
	v_lshlrev_b64 v[32:33], 13, v[32:33]
	s_waitcnt vmcnt(0)
	v_lshl_add_u64 v[60:61], v[34:35], 0, v[32:33]
	v_add_co_u32_e32 v32, vcc, 0x10000, v60
	s_mov_b64 s[4:5], 0
	s_nop 0
	v_addc_co_u32_e32 v33, vcc, 0, v61, vcc
	v_add_co_u32_e32 v40, vcc, 0x20000, v60
	global_load_dwordx4 v[36:39], v[60:61], off nt
	s_nop 0
	global_load_dwordx4 v[32:35], v[32:33], off nt
	v_addc_co_u32_e32 v41, vcc, 0, v61, vcc
	v_add_co_u32_e32 v42, vcc, 0x30000, v60
	s_nop 1
	v_addc_co_u32_e32 v43, vcc, 0, v61, vcc
	v_add_co_u32_e32 v48, vcc, s90, v60
	global_load_dwordx4 v[44:47], v[40:41], off nt
	s_nop 0
	global_load_dwordx4 v[40:43], v[42:43], off nt
	v_addc_co_u32_e32 v49, vcc, 0, v61, vcc
	v_add_co_u32_e32 v50, vcc, 0x50000, v60
	s_nop 1
	v_addc_co_u32_e32 v51, vcc, 0, v61, vcc
	v_add_co_u32_e32 v56, vcc, 0x60000, v60
	global_load_dwordx4 v[52:55], v[48:49], off nt
	s_nop 0
	global_load_dwordx4 v[48:51], v[50:51], off nt
	v_addc_co_u32_e32 v57, vcc, 0, v61, vcc
	global_load_dwordx4 v[56:59], v[56:57], off nt
	v_lshl_add_u64 v[60:61], v[60:61], 0, s[18:19]

; #define CV_MAP(g_, l_, it_) do { (l_) = lfix; \
;         if (MODE == 2) (it_) = CV_S0 + base + (g_); \
;         else if (MODE == 1) (it_) = cv_ritem(g_); \
;         else if ((g_) < CV_NR) (it_) = cv_ritem(g_); \
;         else { const int q_ = ((g_) - CV_NR) / CV_RPRO; (l_) = 1 + q_; (it_) = cv_ritem(CV_DEFER + ((g_) - CV_NR) - q_ * CV_RPRO); } } while (0)
; template <int MODE>
; __device__ __forceinline__ void cv_jobs(const Frame& F, const Args& a, int lfix, int base, int njobs, int w, int nw) {
;     ...
;         const int g1 = g + nw; int l, it, l1, it1; CV_MAP(g, l, it); CV_MAP(g1, l1, it1);
;         cv_load(a, l, it, F.lane, sa);
;         if (g1 < njobs) cv_load(a, l1, it1, F.lane, sb);
.LBB0_997:
	s_waitcnt vmcnt(0)
	global_load_dwordx4 v[60:63], v[60:61], off nt
	s_cmpk_lt_i32 s9, 0xc00
	s_movk_i32 s4, 0x3220
	s_cselect_b32 s12, 0x400, s4
	s_add_i32 s12, s12, s8
	s_add_i32 s11, s12, 0x3e20
	s_cmpk_lt_i32 s9, 0x2c00
	s_cselect_b64 s[4:5], -1, 0
	s_cmpk_gt_i32 s9, 0x2bff
	s_cbranch_scc1 .LBB0_1013
	s_cmpk_gt_i32 s11, 0x161f
	s_mov_b64 s[6:7], -1
	s_cbranch_scc0 .LBB0_1008
	s_cmpk_gt_u32 s11, 0x1e1f
	s_cbranch_scc0 .LBB0_1005
	s_cmpk_gt_u32 s11, 0x3e1f
	s_cbranch_scc0 .LBB0_1002
	s_and_b32 s6, s12, 0xffffffc0
	v_add_u32_e32 v0, s6, v80
	s_lshl_b32 s6, s12, 7
	s_and_b32 s84, s6, 0x1f80
	v_ashrrev_i32_e32 v1, 31, v0
	v_lshl_add_u64 v[2:3], v[64:65], 0, s[84:85]
	v_lshlrev_b64 v[0:1], 13, v[0:1]
	v_lshl_add_u64 v[0:1], v[2:3], 0, v[0:1]
	s_mov_b64 s[6:7], 0x10000
	v_lshl_add_u64 v[4:5], v[0:1], 0, s[6:7]
	s_mov_b64 s[6:7], 0x20000
	v_lshl_add_u64 v[8:9], v[0:1], 0, s[6:7]
	s_mov_b64 s[6:7], 0x30000
	v_lshl_add_u64 v[12:13], v[0:1], 0, s[6:7]
	s_mov_b64 s[6:7], 0x50000
	v_lshl_add_u64 v[20:21], v[0:1], 0, s[6:7]
	s_mov_b64 s[6:7], 0x60000
	v_lshl_add_u64 v[16:17], v[0:1], 0, s[88:89]
	v_lshl_add_u64 v[24:25], v[0:1], 0, s[6:7]
	v_lshl_add_u64 v[28:29], v[0:1], 0, s[18:19]
	s_mov_b64 s[6:7], 0
